# sliding-window item K/V staging: 5 of the 12 per-load vmcnt(0)+merge moves deferred to one masked tail (exec masks parked in VGPR lanes)
# speedup vs baseline: 1.0152x; 1.0102x over previous
.LBB0_260:
	s_andn2_b64 vcc, exec, s[0:1]
	s_cbranch_vccnz .LBB0_136
	v_readlane_b32 s2, v249, 30
	v_readlane_b32 s3, v249, 31
	s_load_dwordx4 s[72:75], s[2:3], 0x148
	s_lshl_b32 s6, s16, 4
	s_and_b32 s0, s6, 0xffffe000
	s_and_b32 s5, s16, 3
	s_and_b32 s4, s6, 0x1fc0
	s_mul_hi_i32 s1, s0, 0xe00
	s_mulk_i32 s0, 0xe00
	s_load_dwordx2 s[2:3], s[2:3], 0x40
	s_waitcnt lgkmcnt(0)
	s_add_u32 s0, s72, s0
	s_mul_i32 s7, s5, 3
	v_readlane_b32 s8, v249, 55
	s_addc_u32 s1, s73, s1
	v_readlane_b32 s9, v249, 56
	s_add_i32 s8, s7, s8
	s_ashr_i32 s9, s8, 31
	s_lshl_b64 s[8:9], s[8:9], 2
	s_add_u32 s2, s2, s8
	s_addc_u32 s3, s3, s9
	global_load_dwordx3 v[72:74], v80, s[2:3]
	v_writelane_b32 v250, 0, 0
	v_writelane_b32 v250, 0, 1
	v_writelane_b32 v250, 0, 2
	v_writelane_b32 v250, 0, 3
	v_writelane_b32 v250, 0, 4
	v_writelane_b32 v250, 0, 5
	v_writelane_b32 v250, 0, 6
	v_writelane_b32 v250, 0, 7
	v_writelane_b32 v250, 0, 8
	v_writelane_b32 v250, 0, 9
	v_writelane_b32 v250, 0, 10
	v_writelane_b32 v250, 0, 11
	v_writelane_b32 v250, 0, 12
	v_writelane_b32 v250, 0, 13
	v_writelane_b32 v250, 0, 14
	v_writelane_b32 v250, 0, 15
	v_writelane_b32 v250, 0, 16
	v_writelane_b32 v250, 0, 17
	v_writelane_b32 v250, 0, 18
	v_writelane_b32 v250, 0, 19
	v_writelane_b32 v250, 0, 20
	v_writelane_b32 v250, 0, 21
	v_writelane_b32 v250, 0, 22
	v_writelane_b32 v250, 0, 23
	v_mov_b32_e32 v5, v220
	s_add_i32 s7, s4, 0xffffff80
	v_ashrrev_i32_e32 v11, 3, v5
	v_add_u32_e32 v12, s7, v11
	v_cmp_gt_i32_e32 vcc, 0, v12
	s_and_saveexec_b64 s[2:3], vcc
	s_xor_b64 s[2:3], exec, s[2:3]
	s_cbranch_execz .LBB0_263
	v_mov_b32_e32 v4, v80
	s_nop 0
	v_mov_b64_e32 v[0:1], v[4:5]
	v_mov_b64_e32 v[2:3], v[6:7]

.LBB0_271:
	s_or_saveexec_b64 s[2:3], s[2:3]
	v_mov_b32_e32 v14, v16
	v_mov_b32_e32 v15, v16
	s_xor_b64 exec, exec, s[2:3]
	s_cbranch_execz .LBB0_273
	v_mov_b64_e32 v[12:13], s[0:1]
	v_mad_u64_u32 v[12:13], s[8:9], v1, s46, v[12:13]
	v_readlane_b32 s8, v249, 19
	v_readlane_b32 s9, v249, 20
	s_mov_b32 s11, s9
	s_lshl_b32 s10, s5, 7
	v_lshl_add_u64 v[12:13], v[12:13], 0, s[10:11]
	v_mov_b32_e32 v77, v80
	v_lshl_add_u64 v[12:13], v[12:13], 0, v[76:77]
	global_load_dwordx4 v[12:15], v[12:13], off offset:1536
	v_writelane_b32 v249, s8, 19
	v_writelane_b32 v250, exec_lo, 4
	v_writelane_b32 v250, exec_hi, 5
	s_nop 0
	v_writelane_b32 v249, s9, 20

.LBB0_279:
	s_or_saveexec_b64 s[2:3], s[2:3]
	v_mov_b32_e32 v26, v28
	v_mov_b32_e32 v27, v28
	s_xor_b64 exec, exec, s[2:3]
	s_cbranch_execz .LBB0_281
	v_mov_b64_e32 v[24:25], s[0:1]
	v_mad_u64_u32 v[24:25], s[8:9], v1, s46, v[24:25]
	v_readlane_b32 s8, v249, 19
	v_readlane_b32 s9, v249, 20
	s_mov_b32 s11, s9
	s_lshl_b32 s10, s5, 7
	v_lshl_add_u64 v[24:25], v[24:25], 0, s[10:11]
	v_mov_b32_e32 v77, v80
	v_lshl_add_u64 v[24:25], v[24:25], 0, v[76:77]
	global_load_dwordx4 v[24:27], v[24:25], off offset:1536
	v_writelane_b32 v249, s8, 19
	v_writelane_b32 v250, exec_lo, 8
	v_writelane_b32 v250, exec_hi, 9
	s_nop 0
	v_writelane_b32 v249, s9, 20

.LBB0_291:
	s_or_saveexec_b64 s[2:3], s[2:3]
	v_mov_b32_e32 v42, v44
	v_mov_b32_e32 v43, v44
	s_xor_b64 exec, exec, s[2:3]
	s_cbranch_execz .LBB0_293
	v_mov_b64_e32 v[40:41], s[0:1]
	v_mad_u64_u32 v[40:41], s[8:9], v1, s46, v[40:41]
	v_readlane_b32 s8, v249, 19
	v_readlane_b32 s9, v249, 20
	s_mov_b32 s11, s9
	s_lshl_b32 s10, s5, 7
	v_lshl_add_u64 v[40:41], v[40:41], 0, s[10:11]
	v_mov_b32_e32 v77, v80
	v_lshl_add_u64 v[40:41], v[40:41], 0, v[76:77]
	global_load_dwordx4 v[40:43], v[40:41], off offset:2048
	v_writelane_b32 v249, s8, 19
	v_writelane_b32 v250, exec_lo, 14
	v_writelane_b32 v250, exec_hi, 15
	s_nop 0
	v_writelane_b32 v249, s9, 20

.LBB0_299:
	s_or_saveexec_b64 s[2:3], s[2:3]
	v_mov_b32_e32 v54, v56
	v_mov_b32_e32 v55, v56
	s_xor_b64 exec, exec, s[2:3]
	s_cbranch_execz .LBB0_301
	v_mov_b64_e32 v[52:53], s[0:1]
	v_mad_u64_u32 v[52:53], s[8:9], v1, s46, v[52:53]
	v_readlane_b32 s8, v249, 19
	v_readlane_b32 s9, v249, 20
	s_mov_b32 s11, s9
	s_lshl_b32 s10, s5, 7
	v_lshl_add_u64 v[52:53], v[52:53], 0, s[10:11]
	v_mov_b32_e32 v77, v80
	v_lshl_add_u64 v[52:53], v[52:53], 0, v[76:77]
	global_load_dwordx4 v[52:55], v[52:53], off offset:2048
	v_writelane_b32 v249, s8, 19
	v_writelane_b32 v250, exec_lo, 18
	v_writelane_b32 v250, exec_hi, 19
	s_nop 0
	v_writelane_b32 v249, s9, 20

.LBB0_307:
	s_or_saveexec_b64 s[2:3], s[2:3]
	v_mov_b32_e32 v66, v68
	v_mov_b32_e32 v67, v68
	s_xor_b64 exec, exec, s[2:3]
	s_cbranch_execz .LBB0_309
	v_mov_b64_e32 v[64:65], s[0:1]
	v_mad_u64_u32 v[64:65], s[0:1], v1, s46, v[64:65]
	v_readlane_b32 s0, v249, 19
	v_readlane_b32 s1, v249, 20
	s_mov_b32 s9, s1
	s_lshl_b32 s8, s5, 7
	v_lshl_add_u64 v[64:65], v[64:65], 0, s[8:9]
	v_mov_b32_e32 v77, v80
	v_lshl_add_u64 v[64:65], v[64:65], 0, v[76:77]
	global_load_dwordx4 v[64:67], v[64:65], off offset:2048
	v_writelane_b32 v249, s0, 19
	v_writelane_b32 v250, exec_lo, 22
	v_writelane_b32 v250, exec_hi, 23
	s_nop 0
	v_writelane_b32 v249, s1, 20
.LBB0_309:
	s_movk_i32 s8, 0xe00
	s_or_b64 exec, exec, s[2:3]
	s_waitcnt vmcnt(0)
	v_writelane_b32 v250, exec_lo, 30
	v_writelane_b32 v250, exec_hi, 31
	s_nop 0
	v_readlane_b32 s2, v250, 4
	v_readlane_b32 s3, v250, 5
	s_mov_b64 exec, s[2:3]
	v_mov_b32_e32 v16, v13
	v_readlane_b32 s2, v250, 8
	v_readlane_b32 s3, v250, 9
	s_mov_b64 exec, s[2:3]
	v_mov_b32_e32 v28, v25
	v_readlane_b32 s2, v250, 14
	v_readlane_b32 s3, v250, 15
	s_mov_b64 exec, s[2:3]
	v_mov_b32_e32 v44, v41
	v_readlane_b32 s2, v250, 18
	v_readlane_b32 s3, v250, 19
	s_mov_b64 exec, s[2:3]
	v_mov_b32_e32 v56, v53
	v_readlane_b32 s2, v250, 22
	v_readlane_b32 s3, v250, 23
	s_mov_b64 exec, s[2:3]
	v_mov_b32_e32 v68, v65
	v_readlane_b32 s2, v250, 30
	v_readlane_b32 s3, v250, 31
	s_mov_b64 exec, s[2:3]
	s_movk_i32 s0, 0x20e
	s_movk_i32 s2, 0x90
	v_mov_b32_e32 v13, v16
	v_mov_b32_e32 v1, v4
	v_mad_u32_u24 v4, v17, s0, v76
	v_mad_u64_u32 v[16:17], s[0:1], v11, s2, v[76:77]
	ds_write_b128 v16, v[0:3]
	v_lshl_add_u32 v0, v11, 1, v4
	ds_write_b16 v0, v6 offset:36864
	ds_write_b16_d16_hi v0, v6 offset:37392
	ds_write_b16 v0, v10 offset:37920
	ds_write_b16_d16_hi v0, v10 offset:38448
	ds_write_b16 v0, v8 offset:38976
	ds_write_b16_d16_hi v0, v8 offset:39504
	ds_write_b16 v0, v9 offset:40032
	ds_write_b16_d16_hi v0, v9 offset:40560
	v_mad_u64_u32 v[0:1], s[0:1], v7, s2, v[76:77]
	ds_write_b128 v0, v[12:15]
	v_lshl_add_u32 v0, v7, 1, v4
	v_mov_b32_e32 v25, v28
	ds_write_b16 v0, v18 offset:36864
	ds_write_b16_d16_hi v0, v18 offset:37392
	ds_write_b16 v0, v22 offset:37920
	ds_write_b16_d16_hi v0, v22 offset:38448
	ds_write_b16 v0, v20 offset:38976
	ds_write_b16_d16_hi v0, v20 offset:39504
	ds_write_b16 v0, v21 offset:40032
	ds_write_b16_d16_hi v0, v21 offset:40560
	v_mad_u64_u32 v[0:1], s[0:1], v19, s2, v[76:77]
	ds_write_b128 v0, v[24:27]
	v_lshl_add_u32 v0, v19, 1, v4
	v_mov_b32_e32 v37, v46
	ds_write_b16 v0, v30 offset:36864
	ds_write_b16_d16_hi v0, v30 offset:37392
	ds_write_b16 v0, v34 offset:37920
	ds_write_b16_d16_hi v0, v34 offset:38448
	ds_write_b16 v0, v32 offset:38976
	ds_write_b16_d16_hi v0, v32 offset:39504
	ds_write_b16 v0, v33 offset:40032
	ds_write_b16_d16_hi v0, v33 offset:40560
	v_mad_u64_u32 v[0:1], s[0:1], v23, s2, v[76:77]
	ds_write_b128 v0, v[36:39]
	v_lshl_add_u32 v0, v23, 1, v4
	v_mov_b32_e32 v49, v58
	ds_write_b16 v0, v40 offset:36864
	ds_write_b16_d16_hi v0, v40 offset:37392
	ds_write_b16 v0, v44 offset:37920
	ds_write_b16_d16_hi v0, v44 offset:38448
	ds_write_b16 v0, v42 offset:38976
	ds_write_b16_d16_hi v0, v42 offset:39504
	ds_write_b16 v0, v43 offset:40032
	ds_write_b16_d16_hi v0, v43 offset:40560
	v_mad_u64_u32 v[0:1], s[0:1], v29, s2, v[76:77]
	ds_write_b128 v0, v[48:51]
	v_lshl_add_u32 v0, v29, 1, v4
	v_mov_b32_e32 v61, v70
	ds_write_b16 v0, v52 offset:36864
	ds_write_b16_d16_hi v0, v52 offset:37392
	ds_write_b16 v0, v56 offset:37920
	ds_write_b16_d16_hi v0, v56 offset:38448
	ds_write_b16 v0, v54 offset:38976
	ds_write_b16_d16_hi v0, v54 offset:39504
	ds_write_b16 v0, v55 offset:40032
	ds_write_b16_d16_hi v0, v55 offset:40560
	v_mad_u64_u32 v[0:1], s[0:1], v31, s2, v[76:77]
	ds_write_b128 v0, v[60:63]
	v_lshl_add_u32 v0, v31, 1, v4
	ds_write_b16 v0, v64 offset:36864
	ds_write_b16_d16_hi v0, v64 offset:37392
	ds_write_b16 v0, v68 offset:37920
	ds_write_b16_d16_hi v0, v68 offset:38448
	ds_write_b16 v0, v66 offset:38976
	ds_write_b16_d16_hi v0, v66 offset:39504
	ds_write_b16 v0, v67 offset:40032
	ds_write_b16_d16_hi v0, v67 offset:40560
	v_ashrrev_i32_e32 v0, 2, v5
	v_and_b32_e32 v0, -16, v0
	s_waitcnt lgkmcnt(0)
	s_barrier
	v_cmp_gt_i32_e32 vcc, 64, v0
	s_mov_b64 s[0:1], exec
	v_writelane_b32 v249, s0, 61
	s_nop 1
	v_writelane_b32 v249, s1, 62
	s_and_b64 s[0:1], s[0:1], vcc
	s_mov_b64 exec, s[0:1]
	s_cbranch_execz .LBB0_135
	s_and_b32 s2, s6, 0xffffffc0
	s_ashr_i32 s3, s2, 31
	s_mul_i32 s1, s2, 0xe00
	v_and_b32_e32 v6, 64, v229
	s_mul_hi_i32 s0, s2, 0xe00
	s_add_u32 s1, s72, s1
	v_xor_b32_e32 v3, 16, v229
	v_add_u32_e32 v6, 64, v6
	s_addc_u32 s7, s73, s0
	s_mul_i32 s6, s5, 0x180
	v_bfe_u32 v4, v5, 4, 2
	v_cmp_lt_i32_e32 vcc, v3, v6
	s_add_u32 s0, s1, s6
	v_and_b32_e32 v5, 15, v5
	v_lshl_or_b32 v2, v4, 2, v231
	v_cndmask_b32_e32 v7, v229, v3, vcc
	v_xor_b32_e32 v3, 32, v229
	s_addc_u32 s1, s7, 0
	v_or_b32_e32 v8, v0, v5
	v_cmp_lt_i32_e32 vcc, v3, v6
	v_add_u32_e32 v11, s4, v2
	v_mov_b64_e32 v[0:1], s[0:1]
	v_cndmask_b32_e32 v6, v229, v3, vcc
	v_sub_u32_e32 v3, v8, v2
	s_movk_i32 s7, 0x80
	v_add_u32_e32 v10, s4, v8
	v_cmp_lt_i32_e64 s[0:1], -1, v11
	v_cmp_le_i32_e64 s[4:5], v2, v8
	v_cmp_gt_i32_e32 vcc, s7, v3
	s_and_b64 s[4:5], s[4:5], s[0:1]
	s_and_b64 s[4:5], s[4:5], vcc
	v_writelane_b32 v249, s4, 63
	v_cmp_lt_i32_e32 vcc, v2, v8
	v_sub_u32_e32 v2, v2, v8
	v_writelane_b32 v248, s5, 0
	s_movk_i32 s4, 0xff7f
	v_cmp_lt_i32_e64 s[4:5], s4, v2
	s_and_b64 s[4:5], s[0:1], s[4:5]
	s_and_b64 s[4:5], s[4:5], vcc
	v_or_b32_e32 v2, 2, v11
	v_writelane_b32 v248, s4, 1
	v_cmp_ge_i32_e32 vcc, v10, v2
	v_sub_u32_e32 v2, v10, v2
	v_writelane_b32 v248, s5, 2
	s_and_b64 s[4:5], s[0:1], vcc
	v_cmp_gt_i32_e32 vcc, s7, v2
	s_and_b64 s[4:5], s[4:5], vcc
	v_or_b32_e32 v2, 3, v11
	v_writelane_b32 v248, s4, 3
	v_cmp_ge_i32_e32 vcc, v10, v2
	v_sub_u32_e32 v2, v10, v2
	v_writelane_b32 v248, s5, 4
	s_and_b64 s[4:5], s[0:1], vcc
	v_cmp_gt_i32_e32 vcc, s7, v2
	s_and_b64 s[4:5], s[4:5], vcc
	v_or_b32_e32 v2, 16, v11
	v_writelane_b32 v248, s4, 5
	v_cmp_ge_i32_e32 vcc, v10, v2
	v_sub_u32_e32 v2, v10, v2
	v_writelane_b32 v248, s5, 6
	s_and_b64 s[4:5], s[0:1], vcc
	v_cmp_gt_i32_e32 vcc, s7, v2
	s_and_b64 s[4:5], s[4:5], vcc
	v_or_b32_e32 v2, 17, v11
	v_writelane_b32 v248, s4, 7
	v_cmp_ge_i32_e32 vcc, v10, v2
	v_sub_u32_e32 v2, v10, v2
	v_writelane_b32 v248, s5, 8
	s_and_b64 s[4:5], s[0:1], vcc
	v_cmp_gt_i32_e32 vcc, s7, v2
	v_or_b32_e32 v2, 18, v11
	s_and_b64 s[10:11], s[4:5], vcc
	v_cmp_ge_i32_e32 vcc, v10, v2
	v_sub_u32_e32 v2, v10, v2
	s_and_b64 s[4:5], s[0:1], vcc
	v_cmp_gt_i32_e32 vcc, s7, v2
	v_or_b32_e32 v2, 19, v11
	s_and_b64 s[12:13], s[4:5], vcc
	v_cmp_ge_i32_e32 vcc, v10, v2
	v_sub_u32_e32 v2, v10, v2
	s_and_b64 s[4:5], s[0:1], vcc
	v_cmp_gt_i32_e32 vcc, s7, v2
	v_or_b32_e32 v2, 32, v11
	s_and_b64 s[14:15], s[4:5], vcc
	v_cmp_ge_i32_e32 vcc, v10, v2
	v_sub_u32_e32 v2, v10, v2
	s_and_b64 s[4:5], s[0:1], vcc
	v_cmp_gt_i32_e32 vcc, s7, v2
	v_or_b32_e32 v2, 33, v11
	s_and_b64 s[16:17], s[4:5], vcc
	v_cmp_ge_i32_e32 vcc, v10, v2
	v_sub_u32_e32 v2, v10, v2
	s_and_b64 s[4:5], s[0:1], vcc
	v_cmp_gt_i32_e32 vcc, s7, v2
	v_or_b32_e32 v2, 34, v11
	s_and_b64 s[18:19], s[4:5], vcc
	v_cmp_ge_i32_e32 vcc, v10, v2
	v_sub_u32_e32 v2, v10, v2
	s_and_b64 s[4:5], s[0:1], vcc
	v_cmp_gt_i32_e32 vcc, s7, v2
	v_or_b32_e32 v2, 35, v11
	s_and_b64 s[20:21], s[4:5], vcc
	v_cmp_ge_i32_e32 vcc, v10, v2
	v_sub_u32_e32 v2, v10, v2
	s_and_b64 s[4:5], s[0:1], vcc
	v_cmp_gt_i32_e32 vcc, s7, v2
	v_or_b32_e32 v2, 48, v11
	s_and_b64 s[22:23], s[4:5], vcc
	v_cmp_ge_i32_e32 vcc, v10, v2
	v_sub_u32_e32 v2, v10, v2
	s_and_b64 s[4:5], s[0:1], vcc
	v_cmp_gt_i32_e32 vcc, s7, v2
	v_or_b32_e32 v2, 49, v11
	s_and_b64 s[24:25], s[4:5], vcc
	v_cmp_ge_i32_e32 vcc, v10, v2
	v_sub_u32_e32 v2, v10, v2
	s_and_b64 s[4:5], s[0:1], vcc
	v_cmp_gt_i32_e32 vcc, s7, v2
	v_or_b32_e32 v2, 50, v11
	s_and_b64 s[26:27], s[4:5], vcc
	v_cmp_ge_i32_e32 vcc, v10, v2
	v_sub_u32_e32 v2, v10, v2
	s_and_b64 s[4:5], s[0:1], vcc
	v_cmp_gt_i32_e32 vcc, s7, v2
	v_or_b32_e32 v2, 51, v11
	s_and_b64 s[4:5], s[4:5], vcc
	v_cmp_ge_i32_e32 vcc, v10, v2
	v_sub_u32_e32 v2, v10, v2
	s_and_b64 s[0:1], s[0:1], vcc
	v_cmp_gt_i32_e32 vcc, s7, v2
	s_and_b64 s[30:31], s[0:1], vcc
	v_add_u32_e32 v2, 64, v11
	s_movk_i32 s0, 0xffbf
	v_cmp_lt_i32_e32 vcc, s0, v11
	v_cmp_ge_i32_e64 s[0:1], v10, v2
	v_sub_u32_e32 v2, v10, v2
	s_and_b64 s[0:1], vcc, s[0:1]
	v_cmp_gt_i32_e32 vcc, s7, v2
	s_and_b64 s[34:35], s[0:1], vcc
	v_add_u32_e32 v2, 0x41, v11
	s_movk_i32 s0, 0xffbe
	v_cmp_lt_i32_e32 vcc, s0, v11
	v_cmp_ge_i32_e64 s[0:1], v10, v2
	v_sub_u32_e32 v2, v10, v2
	s_and_b64 s[0:1], vcc, s[0:1]
	v_cmp_gt_i32_e32 vcc, s7, v2
	s_and_b64 s[36:37], s[0:1], vcc
	v_add_u32_e32 v2, 0x42, v11
	s_movk_i32 s0, 0xffbd
	v_cmp_lt_i32_e32 vcc, s0, v11
	v_cmp_ge_i32_e64 s[0:1], v10, v2
	v_sub_u32_e32 v2, v10, v2
	s_and_b64 s[0:1], vcc, s[0:1]
	v_cmp_gt_i32_e32 vcc, s7, v2
	s_and_b64 s[38:39], s[0:1], vcc
	v_add_u32_e32 v2, 0x43, v11
	s_movk_i32 s0, 0xffbc
	v_cmp_lt_i32_e32 vcc, s0, v11
	v_cmp_ge_i32_e64 s[0:1], v10, v2
	v_sub_u32_e32 v2, v10, v2
	s_and_b64 s[0:1], vcc, s[0:1]
	v_cmp_gt_i32_e32 vcc, s7, v2
	s_and_b64 s[40:41], s[0:1], vcc
	v_add_u32_e32 v2, 0x50, v11
	s_movk_i32 s0, 0xffaf
	v_cmp_lt_i32_e32 vcc, s0, v11
	v_cmp_ge_i32_e64 s[0:1], v10, v2
	v_sub_u32_e32 v2, v10, v2
	s_and_b64 s[0:1], vcc, s[0:1]
	v_cmp_gt_i32_e32 vcc, s7, v2
	s_and_b64 s[42:43], s[0:1], vcc
	v_add_u32_e32 v2, 0x51, v11
	s_movk_i32 s0, 0xffae
	v_cmp_lt_i32_e32 vcc, s0, v11
	v_cmp_ge_i32_e64 s[0:1], v10, v2
	v_sub_u32_e32 v2, v10, v2
	s_and_b64 s[0:1], vcc, s[0:1]
	v_cmp_gt_i32_e32 vcc, s7, v2
	s_and_b64 s[44:45], s[0:1], vcc
	v_add_u32_e32 v2, 0x52, v11
	s_movk_i32 s0, 0xffad
	v_cmp_lt_i32_e32 vcc, s0, v11
	v_cmp_ge_i32_e64 s[0:1], v10, v2
	v_sub_u32_e32 v2, v10, v2
	s_and_b64 s[0:1], vcc, s[0:1]
	v_cmp_gt_i32_e32 vcc, s7, v2
	s_and_b64 s[46:47], s[0:1], vcc
	v_add_u32_e32 v2, 0x53, v11
	s_movk_i32 s0, 0xffac
	v_cmp_lt_i32_e32 vcc, s0, v11
	v_cmp_ge_i32_e64 s[0:1], v10, v2
	v_sub_u32_e32 v2, v10, v2
	s_and_b64 s[0:1], vcc, s[0:1]
	v_cmp_gt_i32_e32 vcc, s7, v2
	s_and_b64 s[48:49], s[0:1], vcc
	v_add_u32_e32 v2, 0x60, v11
	s_movk_i32 s0, 0xff9f
	v_cmp_lt_i32_e32 vcc, s0, v11
	v_cmp_ge_i32_e64 s[0:1], v10, v2
	v_sub_u32_e32 v2, v10, v2
	s_and_b64 s[0:1], vcc, s[0:1]
	v_cmp_gt_i32_e32 vcc, s7, v2
	s_and_b64 s[50:51], s[0:1], vcc
	v_add_u32_e32 v2, 0x61, v11
	s_movk_i32 s0, 0xff9e
	v_cmp_lt_i32_e32 vcc, s0, v11
	v_cmp_ge_i32_e64 s[0:1], v10, v2
	v_sub_u32_e32 v2, v10, v2
	s_and_b64 s[0:1], vcc, s[0:1]
	v_cmp_gt_i32_e32 vcc, s7, v2
	s_and_b64 s[52:53], s[0:1], vcc
	v_add_u32_e32 v2, 0x62, v11
	s_movk_i32 s0, 0xff9d
	v_cmp_lt_i32_e32 vcc, s0, v11
	v_cmp_ge_i32_e64 s[0:1], v10, v2
	v_sub_u32_e32 v2, v10, v2
	s_and_b64 s[0:1], vcc, s[0:1]
	v_cmp_gt_i32_e32 vcc, s7, v2
	s_and_b64 s[54:55], s[0:1], vcc
	v_add_u32_e32 v2, 0x63, v11
	s_movk_i32 s0, 0xff9c
	v_cmp_lt_i32_e32 vcc, s0, v11
	v_cmp_ge_i32_e64 s[0:1], v10, v2
	v_sub_u32_e32 v2, v10, v2
	s_and_b64 s[0:1], vcc, s[0:1]
	v_cmp_gt_i32_e32 vcc, s7, v2
	s_and_b64 s[56:57], s[0:1], vcc
	v_add_u32_e32 v2, 0x70, v11
	s_movk_i32 s0, 0xff8f
	v_cmp_lt_i32_e32 vcc, s0, v11
	v_cmp_ge_i32_e64 s[0:1], v10, v2
	v_sub_u32_e32 v2, v10, v2
	s_and_b64 s[0:1], vcc, s[0:1]
	v_cmp_gt_i32_e32 vcc, s7, v2
	s_and_b64 s[58:59], s[0:1], vcc
	v_add_u32_e32 v2, 0x71, v11
	s_movk_i32 s0, 0xff8e
	v_cmp_lt_i32_e32 vcc, s0, v11
	v_cmp_ge_i32_e64 s[0:1], v10, v2
	v_sub_u32_e32 v2, v10, v2
	s_and_b64 s[0:1], vcc, s[0:1]
	v_cmp_gt_i32_e32 vcc, s7, v2
	s_and_b64 s[60:61], s[0:1], vcc
	v_add_u32_e32 v2, 0x72, v11
	s_movk_i32 s0, 0xff8d
	v_cmp_lt_i32_e32 vcc, s0, v11
	v_cmp_ge_i32_e64 s[0:1], v10, v2
	v_sub_u32_e32 v2, v10, v2
	s_and_b64 s[0:1], vcc, s[0:1]
	v_cmp_gt_i32_e32 vcc, s7, v2
	s_and_b64 s[62:63], s[0:1], vcc
	v_add_u32_e32 v2, 0x73, v11
	s_movk_i32 s0, 0xff8c
	v_cmp_lt_i32_e32 vcc, s0, v11
	v_cmp_ge_i32_e64 s[0:1], v10, v2
	v_sub_u32_e32 v2, v10, v2
	s_and_b64 s[0:1], vcc, s[0:1]
	v_cmp_gt_i32_e32 vcc, s7, v2
	v_add_u32_e32 v2, 0x80, v11
	s_and_b64 s[64:65], s[0:1], vcc
	v_cmp_ge_i32_e32 vcc, v10, v2
	v_sub_u32_e32 v2, v10, v2
	v_cmp_gt_i32_e64 s[0:1], s7, v2
	v_add_u32_e32 v2, 0x81, v11
	s_and_b64 s[66:67], vcc, s[0:1]
	v_cmp_ge_i32_e32 vcc, v10, v2
	v_sub_u32_e32 v2, v10, v2
	v_cmp_gt_i32_e64 s[0:1], s7, v2
	v_add_u32_e32 v2, 0x82, v11
	s_and_b64 s[68:69], vcc, s[0:1]
	v_sub_u32_e32 v3, v10, v2
	v_cmp_ge_i32_e32 vcc, v10, v2
	v_add_u32_e32 v2, 0x83, v11
	v_cmp_gt_i32_e64 s[0:1], s7, v3
	v_sub_u32_e32 v3, v10, v2
	s_and_b64 s[70:71], vcc, s[0:1]
	v_cmp_ge_i32_e32 vcc, v10, v2
	v_cmp_gt_i32_e64 s[0:1], s7, v3
	v_ashrrev_i32_e32 v9, 31, v8
	s_and_b64 s[72:73], vcc, s[0:1]
	s_lshl_b64 s[0:1], s[2:3], 11
	v_lshlrev_b64 v[2:3], 11, v[8:9]
	v_lshl_add_u64 v[2:3], s[0:1], 0, v[2:3]
	v_lshlrev_b32_e32 v9, 3, v4
	v_or3_b32 v2, v2, s6, v9
	v_add_u32_e32 v12, 0x90, v11
	v_lshl_add_u64 v[60:61], s[74:75], 0, v[2:3]
	v_sub_u32_e32 v2, v10, v12
	v_cmp_ge_i32_e32 vcc, v10, v12
	v_cmp_gt_i32_e64 s[0:1], s7, v2
	v_add_u32_e32 v2, 0x91, v11
	s_and_b64 s[74:75], vcc, s[0:1]
	v_cmp_ge_i32_e32 vcc, v10, v2
	v_sub_u32_e32 v2, v10, v2
	v_cmp_gt_i32_e64 s[0:1], s7, v2
	v_add_u32_e32 v2, 0x92, v11
	s_and_b64 s[76:77], vcc, s[0:1]
	v_sub_u32_e32 v3, v10, v2
	v_cmp_ge_i32_e32 vcc, v10, v2
	v_add_u32_e32 v2, 0x93, v11
	v_cmp_gt_i32_e64 s[0:1], s7, v3
	v_sub_u32_e32 v3, v10, v2
	s_and_b64 s[78:79], vcc, s[0:1]
	v_cmp_ge_i32_e32 vcc, v10, v2
	v_cmp_gt_i32_e64 s[0:1], s7, v3
	v_add_u32_e32 v2, 0xa0, v11
	s_and_b64 s[80:81], vcc, s[0:1]
	v_sub_u32_e32 v3, v10, v2
	v_cmp_ge_i32_e32 vcc, v10, v2
	v_add_u32_e32 v2, 0xa1, v11
	v_cmp_gt_i32_e64 s[0:1], s7, v3
	v_sub_u32_e32 v3, v10, v2
	s_and_b64 s[82:83], vcc, s[0:1]
	v_cmp_ge_i32_e32 vcc, v10, v2
	v_cmp_gt_i32_e64 s[0:1], s7, v3
	v_add_u32_e32 v2, 0xa2, v11
	s_and_b64 s[84:85], vcc, s[0:1]
	v_sub_u32_e32 v3, v10, v2
	v_cmp_ge_i32_e32 vcc, v10, v2
	v_add_u32_e32 v2, 0xa3, v11
	v_cmp_gt_i32_e64 s[0:1], s7, v3
	v_sub_u32_e32 v3, v10, v2
	s_and_b64 s[86:87], vcc, s[0:1]
	v_cmp_ge_i32_e32 vcc, v10, v2
	v_cmp_gt_i32_e64 s[0:1], s7, v3
	v_add_u32_e32 v2, 0xb0, v11
	s_and_b64 s[88:89], vcc, s[0:1]
	v_sub_u32_e32 v3, v10, v2
	v_cmp_ge_i32_e32 vcc, v10, v2
	v_add_u32_e32 v2, 0xb1, v11
	v_cmp_gt_i32_e64 s[0:1], s7, v3
	v_sub_u32_e32 v3, v10, v2
	s_and_b64 s[90:91], vcc, s[0:1]
	v_cmp_ge_i32_e32 vcc, v10, v2
	v_cmp_gt_i32_e64 s[0:1], s7, v3
	v_add_u32_e32 v2, 0xb2, v11
	s_and_b64 s[92:93], vcc, s[0:1]
	v_sub_u32_e32 v3, v10, v2
	v_cmp_ge_i32_e32 vcc, v10, v2
	v_add_u32_e32 v2, 0xb3, v11
	v_cmp_gt_i32_e64 s[0:1], s7, v3
	v_sub_u32_e32 v3, v10, v2
	s_and_b64 s[94:95], vcc, s[0:1]
	v_cmp_ge_i32_e32 vcc, v10, v2
	v_cmp_gt_i32_e64 s[0:1], s7, v3
	s_and_b64 s[96:97], vcc, s[0:1]
	v_mad_i64_i32 v[0:1], s[0:1], v8, s8, v[0:1]
	v_lshlrev_b32_e32 v2, 4, v4
	v_mov_b32_e32 v3, v80
	v_lshl_add_u64 v[62:63], v[0:1], 0, v[2:3]
	global_load_dwordx4 v[16:19], v[62:63], off offset:64
	global_load_dwordx4 v[32:35], v[62:63], off
	v_sub_u32_e32 v0, v2, v9
	v_mul_u32_u24_e32 v1, 0x90, v5
	v_mul_u32_u24_e32 v3, 0x210, v5
	v_lshlrev_b32_e32 v64, 2, v7
	v_lshlrev_b32_e32 v65, 2, v6
	v_add_u32_e32 v66, v2, v1
	v_add_u32_e32 v67, v0, v3
	s_mov_b32 s6, 0
	v_cmp_gt_i32_e64 s[0:1], 64, v8
	s_mov_b64 s[2:3], 0
	s_waitcnt vmcnt(1)
	v_mov_b64_e32 v[0:1], v[16:17]
	s_waitcnt vmcnt(0)
	v_mov_b64_e32 v[4:5], v[32:33]
	v_mov_b64_e32 v[2:3], v[18:19]
	v_mov_b64_e32 v[6:7], v[34:35]
	s_branch .LBB0_312
